# GLA scan: next-chunk LDS staging right after the second barrier, output-base scalar math moved off the loop top
# speedup vs baseline: 1.0205x; 1.0005x over previous
; __device__ __forceinline__ void gla_scan_phase(const Params& p, int j, bool need_ctx, char* smem, int tid, int bid) {
;     ...
;   for (int unit = bid; unit < 256; unit += gridDim.x) {
;     int dir, dvs, h, b;
;     if (gridDim.x == 256) { const int g = (unit & 7) * 8 + (unit >> 5); dvs = (unit >> 3) & 3; dir = g & 1; h = (g >> 1) & 3; b = g >> 3; }
;     else { dir = unit & 1; dvs = (unit >> 1) & 3; h = (unit >> 3) & 3; b = unit >> 5; }
;     const int dvc = tid & 63, tg = tid >> 6;
;     f32x16 Sacc;
; #pragma unroll
;     for (int r = 0; r < 16; ++r) Sacc[r] = 0.f;
;     __syncthreads();
;     { u32x4 z = {0u, 0u, 0u, 0u}; *(u32x4*)(STL + tid * 32) = z; *(u32x4*)(STL + tid * 32 + 16) = z; }
;     u32x4 qx[2], kx[2]; unsigned kt[16], vv[8]; float ebv = 0.f;
;     const u16* QB = (const u16*)(p.ws + OFF_GQB);
;     const u16* KB2 = (const u16*)((const char*)p.out + OUT_GKB);
;     const float* EBE = (const float*)((const char*)p.out + OUT_EBE);
;     const u16* qsrc = dir ? QB + h * 128 : P + h * 128;
;     const u16* ksrc = dir ? KB2 + h * 128 : P + 512 + h * 128;
;     const long rst = dir ? 512 : LDP;
;     const long sgn = dir ? -1 : 1;
;     ...
;     GLA_PREFETCH(0);
;     for (int ci = 0; ci < 68; ++ci) {
;       asm volatile("" : "+v"(tid));
;       const int lane = tid & 63, wid = tid >> 6, l32 = lane & 31, hi = lane >> 5;
;       const int tbg = wid >> 2, kd = (wid & 3) * 32 + l32;
;       const int dvc = tid & 63, tg = tid >> 6;
;       const bool is_ctx = ci < 4; const int c = is_ctx ? ci : ci - 4; const int TT = is_ctx ? CTXL : SEQL;
;       const int base = is_ctx ? ML + b * CTXL : b * SEQL;
;       char* vT = vT0 + (ci & 1) * 40960;
;       {
;         if (tid < 128) ebend[tid] = ebv;
;         const int r = tid >> 3, c0 = tid & 7;
;         *(u32x4*)(qbL + swz256(r, c0)) = qx[0]; *(u32x4*)(qbL + swz256(r, c0 + 8)) = qx[1];
;         *(u32x4*)(kinvL + swz256(r, c0)) = kx[0]; *(u32x4*)(kinvL + swz256(r, c0 + 8)) = kx[1];
;         const int kdt = tid & 127, tgk = tid >> 7;
;         u32x4 w0 = {kt[0] | (kt[1] << 16), kt[2] | (kt[3] << 16), kt[4] | (kt[5] << 16), kt[6] | (kt[7] << 16)};
;         u32x4 w1 = {kt[8] | (kt[9] << 16), kt[10] | (kt[11] << 16), kt[12] | (kt[13] << 16), kt[14] | (kt[15] << 16)};
;         *(u32x4*)(kendT + swz128(kdt, tgk)) = w0;
;         *(u32x4*)(kendT + swz128(kdt, tgk + 4)) = w1;
.Lgs_roles_done:
	s_waitcnt vmcnt(0) lgkmcnt(0)
	s_barrier
	v_lshlrev_b32_e32 v198, 5, v203
	v_add_u32_e32 v198, 0x12000, v198
	v_mov_b32_e32 v112, 0
	v_mov_b32_e32 v113, 0
	v_mov_b32_e32 v114, 0
	v_mov_b32_e32 v115, 0
	ds_write_b128 v198, v[112:115]
	ds_write_b128 v198, v[112:115] offset:16
	v_mov_b32_e32 v0, 0
	v_mov_b32_e32 v1, 0
	v_mov_b32_e32 v2, 0
	v_mov_b32_e32 v3, 0
	v_mov_b32_e32 v4, 0
	v_mov_b32_e32 v5, 0
	v_mov_b32_e32 v6, 0
	v_mov_b32_e32 v7, 0
	v_mov_b32_e32 v8, 0
	v_mov_b32_e32 v9, 0
	v_mov_b32_e32 v10, 0
	v_mov_b32_e32 v11, 0
	v_mov_b32_e32 v12, 0
	v_mov_b32_e32 v13, 0
	v_mov_b32_e32 v14, 0
	v_mov_b32_e32 v15, 0
	s_mov_b32 s54, 0
	s_add_i32 s1, s54, -4
	s_cmp_lt_u32 s54, 4
	s_cselect_b32 s0, s54, s1
	s_movk_i32 s5, 0x1000
	s_cselect_b32 s1, 0x100, s5
	s_lshl_b32 s4, s35, 8
	s_add_u32 s4, s4, 0x8000
	s_lshl_b32 s5, s35, 12
	s_cmp_lt_u32 s54, 4
	s_cselect_b32 s4, s4, s5
	s_lshl_b32 s0, s0, 6
	s_sub_u32 s1, s1, 64
	s_sub_u32 s1, s1, s0
	s_cmp_eq_u32 s55, 0
	s_cselect_b32 s0, s0, s1
	s_add_u32 s0, s4, s0
	s_mul_i32 s1, s0, s34
	s_add_u32 s6, s22, s1
	s_addc_u32 s7, s23, 0
	s_add_u32 s8, s24, s1
	s_addc_u32 s9, s25, 0
	s_mul_i32 s1, s0, 0x1840
	s_add_u32 s10, s26, s1
	s_addc_u32 s11, s27, 0
	s_lshr_b32 s1, s0, 6
	s_lshl_b32 s1, s1, 11
	s_add_u32 s18, s28, s1
	s_addc_u32 s19, s29, 0
	global_load_dwordx4 v[112:115], v166, s[6:7]
	global_load_dwordx4 v[116:119], v166, s[6:7] offset:128
	global_load_dwordx4 v[120:123], v166, s[8:9]
	global_load_dwordx4 v[124:127], v166, s[8:9] offset:128
	global_load_dwordx4 v[128:131], v183, s[10:11]
	global_load_dword v132, v191, s[18:19]
	s_mov_b32 s65, 1
	s_add_i32 s1, s65, -4
	s_cmp_lt_u32 s65, 4
	s_cselect_b32 s0, s65, s1
	s_movk_i32 s5, 0x1000
	s_cselect_b32 s1, 0x100, s5
	s_lshl_b32 s4, s35, 8
	s_add_u32 s4, s4, 0x8000
	s_lshl_b32 s5, s35, 12
	s_cmp_lt_u32 s65, 4
	s_cselect_b32 s4, s4, s5
	s_lshl_b32 s0, s0, 6
	s_sub_u32 s1, s1, 64
	s_sub_u32 s1, s1, s0
	s_cmp_eq_u32 s55, 0
	s_cselect_b32 s0, s0, s1
	s_add_u32 s0, s4, s0
	s_mul_i32 s1, s0, s34
	s_add_u32 s6, s22, s1
	s_addc_u32 s7, s23, 0
	s_add_u32 s8, s24, s1
	s_addc_u32 s9, s25, 0
	s_mul_i32 s1, s0, 0x1840
	s_add_u32 s10, s26, s1
	s_addc_u32 s11, s27, 0
	s_lshr_b32 s1, s0, 6
	s_lshl_b32 s1, s1, 11
	s_add_u32 s18, s28, s1
	s_addc_u32 s19, s29, 0
	global_load_dwordx4 v[96:99], v166, s[6:7]
	global_load_dwordx4 v[100:103], v166, s[6:7] offset:128
	global_load_dwordx4 v[104:107], v166, s[8:9]
	global_load_dwordx4 v[108:111], v166, s[8:9] offset:128
	global_load_dwordx4 v[136:139], v183, s[10:11]
	global_load_dword v133, v191, s[18:19]
	s_mov_b32 s97, 0
	s_mov_b32 s16, 0
	s_waitcnt vmcnt(6)
	ds_write_b128 v192, v[112:115]
	ds_write_b128 v193, v[116:119]
	ds_write_b128 v143, v[120:123] offset:16384
	ds_write_b128 v144, v[124:127] offset:16384
	ds_write_b128 v196, v[128:131]
	s_cmp_gt_u32 s81, 1
	s_cbranch_scc1 .Lgs_noeb_pro
	ds_write_b32 v197, v132
.Lgs_noeb_pro:
.Lgs_pair:
.Lgs0_chunk:
	s_cmp_gt_u32 s54, 3
	s_cselect_b32 s96, 1, s60
	s_waitcnt lgkmcnt(0)
	s_barrier
	s_add_u32 s65, s54, 2
	s_min_u32 s65, s65, 67
	s_cmp_eq_u32 s96, 0
	s_cbranch_scc1 .Lgs0_nochain
	s_cmp_eq_u32 s76, 1
	s_cbranch_scc1 .Lgs0_nochain
	ds_read_b128 v[32:35], v220
	ds_read_b128 v[48:51], v228
	v_xor_b32_e32 v198, 32, v220
	v_xor_b32_e32 v199, 32, v228
	ds_read_b128 v[36:39], v198
	ds_read_b128 v[52:55], v199
	v_xor_b32_e32 v198, 64, v220
	v_xor_b32_e32 v199, 64, v228
	ds_read_b128 v[40:43], v198
	ds_read_b128 v[56:59], v199
	v_xor_b32_e32 v198, 96, v220
	v_xor_b32_e32 v199, 96, v228
	ds_read_b128 v[44:47], v198
	ds_read_b128 v[60:63], v199
	s_add_i32 s1, s65, -4
	s_cmp_lt_u32 s65, 4
	s_cselect_b32 s0, s65, s1
	s_movk_i32 s5, 0x1000
	s_cselect_b32 s1, 0x100, s5
	s_lshl_b32 s4, s35, 8
	s_add_u32 s4, s4, 0x8000
	s_lshl_b32 s5, s35, 12
	s_cmp_lt_u32 s65, 4
	s_cselect_b32 s4, s4, s5
	s_lshl_b32 s0, s0, 6
	s_sub_u32 s1, s1, 64
	s_sub_u32 s1, s1, s0
	s_cmp_eq_u32 s55, 0
	s_cselect_b32 s0, s0, s1
	s_add_u32 s0, s4, s0
	s_mul_i32 s1, s0, s34
	s_add_u32 s6, s22, s1
	s_addc_u32 s7, s23, 0
	s_add_u32 s8, s24, s1
	s_addc_u32 s9, s25, 0
	s_mul_i32 s1, s0, 0x1840
	s_add_u32 s10, s26, s1
	s_addc_u32 s11, s27, 0
	s_lshr_b32 s1, s0, 6
	s_lshl_b32 s1, s1, 11
	s_add_u32 s18, s28, s1
	s_addc_u32 s19, s29, 0
	s_waitcnt lgkmcnt(6)
	v_mfma_f32_32x32x16_bf16 v[16:31], v[32:35], v[48:51], 0
	v_xor_b32_e32 v198, 128, v220
	v_xor_b32_e32 v199, 128, v228
	ds_read_b128 v[32:35], v198
	ds_read_b128 v[48:51], v199
	global_load_dwordx4 v[112:115], v166, s[6:7]
	s_waitcnt lgkmcnt(6)
	v_mfma_f32_32x32x16_bf16 v[16:31], v[36:39], v[52:55], v[16:31]
	v_xor_b32_e32 v198, 160, v220
	v_xor_b32_e32 v199, 160, v228
	ds_read_b128 v[36:39], v198
	ds_read_b128 v[52:55], v199
	global_load_dwordx4 v[116:119], v166, s[6:7] offset:128
	s_waitcnt lgkmcnt(6)
	v_mfma_f32_32x32x16_bf16 v[16:31], v[40:43], v[56:59], v[16:31]
	v_xor_b32_e32 v198, 192, v220
	v_xor_b32_e32 v199, 192, v228
	ds_read_b128 v[40:43], v198
	ds_read_b128 v[56:59], v199
	global_load_dwordx4 v[120:123], v166, s[8:9]
	s_waitcnt lgkmcnt(6)
	v_mfma_f32_32x32x16_bf16 v[16:31], v[44:47], v[60:63], v[16:31]
	v_xor_b32_e32 v198, 224, v220
	v_xor_b32_e32 v199, 224, v228
	ds_read_b128 v[44:47], v198
	ds_read_b128 v[60:63], v199
	global_load_dwordx4 v[124:127], v166, s[8:9] offset:128
	s_waitcnt lgkmcnt(6)
	v_mfma_f32_32x32x16_bf16 v[16:31], v[32:35], v[48:51], v[16:31]
	ds_read_b64_tr_b16 v[64:65], v140 offset:16384
	ds_read_b64_tr_b16 v[66:67], v141 offset:16384
	ds_read_b64_tr_b16 v[80:81], v142 offset:49152
	ds_read_b64_tr_b16 v[82:83], v142 offset:49664
	global_load_dwordx4 v[128:131], v183, s[10:11]
	s_waitcnt lgkmcnt(8)
	v_mfma_f32_32x32x16_bf16 v[16:31], v[36:39], v[52:55], v[16:31]
	ds_read_b64_tr_b16 v[68:69], v140 offset:20480
	ds_read_b64_tr_b16 v[70:71], v141 offset:20480
	ds_read_b64_tr_b16 v[84:85], v142 offset:51200
	ds_read_b64_tr_b16 v[86:87], v142 offset:51712
	global_load_dword v132, v191, s[18:19]
	s_waitcnt lgkmcnt(10)
	v_mfma_f32_32x32x16_bf16 v[16:31], v[40:43], v[56:59], v[16:31]
	ds_read_b64_tr_b16 v[72:73], v140 offset:24576
	ds_read_b64_tr_b16 v[74:75], v141 offset:24576
	ds_read_b64_tr_b16 v[88:89], v142 offset:53248
	ds_read_b64_tr_b16 v[90:91], v142 offset:53760
	s_waitcnt lgkmcnt(12)
	v_mfma_f32_32x32x16_bf16 v[16:31], v[44:47], v[60:63], v[16:31]
	s_branch .Lgs0_supd

; __device__ __forceinline__ void gla_scan_phase(const Params& p, int j, bool need_ctx, char* smem, int tid, int bid) {
;     ...
; #pragma unroll
;         for (int rg = 0; rg < 4; ++rg) {
;           const f32x4 e4 = *(const f32x4*)(ebend + kb * 32 + 8 * rg + 4 * hi);
;           Sacc[rg * 4 + 0] *= e4[0]; Sacc[rg * 4 + 1] *= e4[1]; Sacc[rg * 4 + 2] *= e4[2]; Sacc[rg * 4 + 3] *= e4[3];
;         }
;       }
;       __syncthreads();
.Lgs0_noscore:
	s_nop 7
	s_nop 3
	s_waitcnt lgkmcnt(0)
	v_mul_f32_e32 v0, v0, v48
	v_mul_f32_e32 v1, v1, v49
	v_mul_f32_e32 v2, v2, v50
	v_mul_f32_e32 v3, v3, v51
	v_mul_f32_e32 v4, v4, v52
	v_mul_f32_e32 v5, v5, v53
	v_mul_f32_e32 v6, v6, v54
	v_mul_f32_e32 v7, v7, v55
	v_mul_f32_e32 v8, v8, v56
	v_mul_f32_e32 v9, v9, v57
	v_mul_f32_e32 v10, v10, v58
	v_mul_f32_e32 v11, v11, v59
	v_mul_f32_e32 v12, v12, v60
	v_mul_f32_e32 v13, v13, v61
	v_mul_f32_e32 v14, v14, v62
	v_mul_f32_e32 v15, v15, v63
	s_barrier
	s_cmp_eq_u32 s97, 0
	s_cbranch_scc1 .Lgs0_w6
	s_waitcnt vmcnt(8)
	s_branch .Lgs0_wd

; __device__ __forceinline__ void gla_scan_phase(const Params& p, int j, bool need_ctx, char* smem, int tid, int bid) {
;     ...
;       if (wid >= 4 && need_o) {
; #pragma unroll
;         for (int k16 = 0; k16 < 4; ++k16) {
;           if (k16 < 2 || tbo == 1) {
;             const bf16x8 a = *(const bf16x8*)(scL + swz128(tbo * 32 + l32, k16 * 2 + hi));
;             const bf16x8 bv = *(const bf16x8*)(vT + swz128(dvbo * 32 + l32, k16 * 2 + hi));
;             oacc = __builtin_amdgcn_mfma_f32_32x32x16_bf16(a, bv, oacc, 0, 0, 0);
;           }
;         }
.Lgs_noeb_b0:
	s_mov_b32 s16, s97
	s_mov_b32 s97, 0
	s_cmp_eq_u32 s96, 0
	s_cbranch_scc1 .Lgs0_state
	s_cmp_eq_u32 s76, 2
	s_cbranch_scc0 .Lgs0_state
	v_xor_b32_e32 v198, 32, v249
	ds_read_b128 v[32:35], v249
	ds_read_b128 v[36:39], v198
	s_cmp_eq_u32 s77, 0
	s_cbranch_scc1 .Lgs0_ohalf
	v_xor_b32_e32 v199, 64, v249
	v_xor_b32_e32 v200, 96, v249
	ds_read_b128 v[40:43], v199
	ds_read_b128 v[44:47], v200
	s_waitcnt lgkmcnt(2)
	v_mfma_f32_32x32x16_bf16 v[16:31], v[80:83], v[32:35], v[16:31]
	v_mfma_f32_32x32x16_bf16 v[16:31], v[84:87], v[36:39], v[16:31]
	s_waitcnt lgkmcnt(0)
	v_mfma_f32_32x32x16_bf16 v[16:31], v[88:91], v[40:43], v[16:31]
	v_mfma_f32_32x32x16_bf16 v[16:31], v[92:95], v[44:47], v[16:31]
	s_branch .Lgs0_ostore

; __device__ __forceinline__ u16 f2bf(float x) { return (u16)(cvtpk(x, 0.f) & 0xffffu); }
; __device__ __forceinline__ int crow(int r, int hi) { return (r & 3) + 8 * (r >> 2) + 4 * hi; }
; __device__ __forceinline__ void gla_scan_phase(const Params& p, int j, bool need_ctx, char* smem, int tid, int bid) {
;     ...
;         if (!is_ctx || need_ctx) {
;           u16* O = dir ? OB : OF;
; #pragma unroll
;           for (int r = 0; r < 16; ++r) {
;             const int pos = c * 64 + tbo * 32 + crow(r, hi);
;             const int tok = dir ? TT - 1 - pos : pos;
;             O[(size_t)(base + tok) * 1024 + h * 256 + dvs * 64 + dvbo * 32 + l32] = f2bf(oacc[r]);
;           }
;         }
;       }
;       {
;         const int dv = dvb2 * 32 + l32;
; #pragma unroll
;         for (int rg = 0; rg < 4; ++rg) {
;           const int k0 = kb * 32 + 8 * rg + 4 * hi;
;           u32x2 w = {cvtpk(Sacc[rg * 4 + 0], Sacc[rg * 4 + 1]), cvtpk(Sacc[rg * 4 + 2], Sacc[rg * 4 + 3])};
;           *(u32x2*)(STL + swz256(dv, k0 >> 3) + (k0 & 7) * 2) = w;
;         }
.Lgs0_ostore:
	v_cvt_pk_bf16_f32 v48, v0, v1
	v_cvt_pk_bf16_f32 v49, v2, v3
	v_cvt_pk_bf16_f32 v50, v4, v5
	v_cvt_pk_bf16_f32 v51, v6, v7
	v_cvt_pk_bf16_f32 v52, v8, v9
	v_cvt_pk_bf16_f32 v53, v10, v11
	v_cvt_pk_bf16_f32 v54, v12, v13
	v_cvt_pk_bf16_f32 v55, v14, v15
	v_xor_b32_e32 v198, 16, v250
	v_xor_b32_e32 v199, 32, v250
	v_xor_b32_e32 v200, 48, v250
	ds_write_b64 v250, v[48:49]
	ds_write_b64 v198, v[50:51]
	ds_write_b64 v199, v[52:53]
	ds_write_b64 v200, v[54:55]
	s_add_i32 s1, s54, -4
	s_cmp_lt_u32 s54, 4
	s_cselect_b32 s0, s54, s1
	s_movk_i32 s5, 0x1000
	s_cselect_b32 s1, 0x100, s5
	s_lshl_b32 s4, s35, 8
	s_add_u32 s4, s4, 0x8000
	s_lshl_b32 s5, s35, 12
	s_cmp_lt_u32 s54, 4
	s_cselect_b32 s4, s4, s5
	s_lshl_b32 s0, s0, 6
	s_sub_u32 s1, s1, 64
	s_sub_u32 s1, s1, s0
	s_cmp_eq_u32 s55, 0
	s_cselect_b32 s0, s0, s1
	s_add_u32 s0, s4, s0
	s_lshl_b32 s1, s0, 11
	s_add_u32 s20, s30, s1
	s_addc_u32 s21, s31, 0
	v_cvt_pk_bf16_f32 v32, v16, v17
	v_cvt_pk_bf16_f32 v33, v18, v19
	v_cvt_pk_bf16_f32 v34, v20, v21
	v_cvt_pk_bf16_f32 v35, v22, v23
	v_cvt_pk_bf16_f32 v36, v24, v25
	v_cvt_pk_bf16_f32 v37, v26, v27
	v_cvt_pk_bf16_f32 v38, v28, v29
	v_cvt_pk_bf16_f32 v39, v30, v31
	s_nop 0
	v_permlane32_swap_b32_e32 v32, v34
	v_permlane32_swap_b32_e32 v33, v35
	v_permlane32_swap_b32_e32 v36, v38
	v_permlane32_swap_b32_e32 v37, v39
	global_store_dwordx4 v204, v[32:35], s[20:21]
	global_store_dwordx4 v204, v[36:39], s[20:21] offset:32
	s_mov_b32 s97, 2
	s_branch .Lgs0_next

; __device__ __forceinline__ void gla_scan_phase(const Params& p, int j, bool need_ctx, char* smem, int tid, int bid) {
;     ...
;       if (ci + 1 < 68) GLA_PREFETCH(ci + 1);
;       __builtin_amdgcn_sched_barrier(0);
;       __syncthreads();
;       f32x16 oacc;
; #pragma unroll
;       for (int r = 0; r < 16; ++r) oacc[r] = 0.f;
;       const int tbo = (wid - 4) >> 1, dvbo = (wid - 4) & 1;
;       const bool need_o = !is_ctx || need_ctx;
;       if (!need_o) {
;       } else if (wid < 4) {
;         const int sb = wid & 1, tb = wid >> 1;
;         if (sb <= tb) {
;           f32x16 sacc;
; #pragma unroll
;           for (int r = 0; r < 16; ++r) sacc[r] = 0.f;
;           bf16x8 av[8], bv8[8];
; #pragma unroll
;           for (int k16 = 0; k16 < 8; ++k16) {
;             av[k16] = *(const bf16x8*)(kinvL + swz256(sb * 32 + l32, k16 * 2 + hi));
;             bv8[k16] = *(const bf16x8*)(qbL + swz256(tb * 32 + l32, k16 * 2 + hi));
;           }
; #pragma unroll
;           for (int k16 = 0; k16 < 8; ++k16) sacc = __builtin_amdgcn_mfma_f32_32x32x16_bf16(av[k16], bv8[k16], sacc, 0, 0, 0);
.Lgs1_chunk:
	s_cmp_gt_u32 s54, 3
	s_cselect_b32 s96, 1, s60
	s_waitcnt lgkmcnt(0)
	s_barrier
	s_add_u32 s65, s54, 2
	s_min_u32 s65, s65, 67
	s_cmp_eq_u32 s96, 0
	s_cbranch_scc1 .Lgs1_nochain
	s_cmp_eq_u32 s76, 1
	s_cbranch_scc1 .Lgs1_nochain
	ds_read_b128 v[32:35], v220
	ds_read_b128 v[48:51], v228
	v_xor_b32_e32 v198, 32, v220
	v_xor_b32_e32 v199, 32, v228
	ds_read_b128 v[36:39], v198
	ds_read_b128 v[52:55], v199
	v_xor_b32_e32 v198, 64, v220
	v_xor_b32_e32 v199, 64, v228
	ds_read_b128 v[40:43], v198
	ds_read_b128 v[56:59], v199
	v_xor_b32_e32 v198, 96, v220
	v_xor_b32_e32 v199, 96, v228
	ds_read_b128 v[44:47], v198
	ds_read_b128 v[60:63], v199
	s_add_i32 s1, s65, -4
	s_cmp_lt_u32 s65, 4
	s_cselect_b32 s0, s65, s1
	s_movk_i32 s5, 0x1000
	s_cselect_b32 s1, 0x100, s5
	s_lshl_b32 s4, s35, 8
	s_add_u32 s4, s4, 0x8000
	s_lshl_b32 s5, s35, 12
	s_cmp_lt_u32 s65, 4
	s_cselect_b32 s4, s4, s5
	s_lshl_b32 s0, s0, 6
	s_sub_u32 s1, s1, 64
	s_sub_u32 s1, s1, s0
	s_cmp_eq_u32 s55, 0
	s_cselect_b32 s0, s0, s1
	s_add_u32 s0, s4, s0
	s_mul_i32 s1, s0, s34
	s_add_u32 s6, s22, s1
	s_addc_u32 s7, s23, 0
	s_add_u32 s8, s24, s1
	s_addc_u32 s9, s25, 0
	s_mul_i32 s1, s0, 0x1840
	s_add_u32 s10, s26, s1
	s_addc_u32 s11, s27, 0
	s_lshr_b32 s1, s0, 6
	s_lshl_b32 s1, s1, 11
	s_add_u32 s18, s28, s1
	s_addc_u32 s19, s29, 0
	s_waitcnt lgkmcnt(6)
	v_mfma_f32_32x32x16_bf16 v[16:31], v[32:35], v[48:51], 0
	v_xor_b32_e32 v198, 128, v220
	v_xor_b32_e32 v199, 128, v228
	ds_read_b128 v[32:35], v198
	ds_read_b128 v[48:51], v199
	global_load_dwordx4 v[96:99], v166, s[6:7]
	s_waitcnt lgkmcnt(6)
	v_mfma_f32_32x32x16_bf16 v[16:31], v[36:39], v[52:55], v[16:31]
	v_xor_b32_e32 v198, 160, v220
	v_xor_b32_e32 v199, 160, v228
	ds_read_b128 v[36:39], v198
	ds_read_b128 v[52:55], v199
	global_load_dwordx4 v[100:103], v166, s[6:7] offset:128
	s_waitcnt lgkmcnt(6)
	v_mfma_f32_32x32x16_bf16 v[16:31], v[40:43], v[56:59], v[16:31]
	v_xor_b32_e32 v198, 192, v220
	v_xor_b32_e32 v199, 192, v228
	ds_read_b128 v[40:43], v198
	ds_read_b128 v[56:59], v199
	global_load_dwordx4 v[104:107], v166, s[8:9]
	s_waitcnt lgkmcnt(6)
	v_mfma_f32_32x32x16_bf16 v[16:31], v[44:47], v[60:63], v[16:31]
	v_xor_b32_e32 v198, 224, v220
	v_xor_b32_e32 v199, 224, v228
	ds_read_b128 v[44:47], v198
	ds_read_b128 v[60:63], v199
	global_load_dwordx4 v[108:111], v166, s[8:9] offset:128
	s_waitcnt lgkmcnt(6)
	v_mfma_f32_32x32x16_bf16 v[16:31], v[32:35], v[48:51], v[16:31]
	ds_read_b64_tr_b16 v[64:65], v140 offset:16384
	ds_read_b64_tr_b16 v[66:67], v141 offset:16384
	ds_read_b64_tr_b16 v[80:81], v142 offset:49152
	ds_read_b64_tr_b16 v[82:83], v142 offset:49664
	global_load_dwordx4 v[136:139], v183, s[10:11]
	s_waitcnt lgkmcnt(8)
	v_mfma_f32_32x32x16_bf16 v[16:31], v[36:39], v[52:55], v[16:31]
	ds_read_b64_tr_b16 v[68:69], v140 offset:20480
	ds_read_b64_tr_b16 v[70:71], v141 offset:20480
	ds_read_b64_tr_b16 v[84:85], v142 offset:51200
	ds_read_b64_tr_b16 v[86:87], v142 offset:51712
	global_load_dword v133, v191, s[18:19]
	s_waitcnt lgkmcnt(10)
	v_mfma_f32_32x32x16_bf16 v[16:31], v[40:43], v[56:59], v[16:31]
	ds_read_b64_tr_b16 v[72:73], v140 offset:24576
	ds_read_b64_tr_b16 v[74:75], v141 offset:24576
	ds_read_b64_tr_b16 v[88:89], v142 offset:53248
	ds_read_b64_tr_b16 v[90:91], v142 offset:53760
	s_waitcnt lgkmcnt(12)
	v_mfma_f32_32x32x16_bf16 v[16:31], v[44:47], v[60:63], v[16:31]
	s_branch .Lgs1_supd
